# Attention PV: transposed V-fragment ds_reads double-buffered in spare VGPRs (dilated and neighbourhood loops fully, differential loop tail) so each MFMA no longer waits a full LDS round trip
# speedup vs baseline: 1.0135x; 1.0023x over previous
; #define LAS __attribute__((address_space(3)))
; __device__ __forceinline__ unsigned pk2(float lo, float hi) { f32x2 v = {lo, hi}; bf16x2_t b = __builtin_convertvector(v, bf16x2_t); return __builtin_bit_cast(unsigned, b); }
; #define MFMA32(a, b, c) __builtin_amdgcn_mfma_f32_32x32x16_bf16((a), (b), (c), 0, 0, 0)
; template <int KSTEPS, class Pol>
; __device__ __forceinline__ void attn_pass(LAS unsigned char* lds, const Pol& P, const bf16_t* qb, int ldq, const bf16_t* kb, int ldk, const bf16_t* vb, int ldv,
;                                           float qs, f32x16 (&O)[4], float& m, float& l) {
;     ...
;             const f32x2 nm = {-mnew, -mnew};
; #pragma unroll
;             for (int i = 0; i < 16; i += 2) { const f32x2 a = (f32x2){S0[i], S0[i + 1]} + nm, b = (f32x2){S1[i], S1[i + 1]} + nm; S0[i] = a.x; S0[i + 1] = a.y; S1[i] = b.x; S1[i + 1] = b.y; }
;         }
;         f32x2 ls2 = {0.f, 0.f};
; #pragma unroll
;         for (int s = 0; s < 4; ++s) {
;             unsigned w[4];
; #pragma unroll
;             for (int e = 0; e < 4; ++e) {
;                 const int i = 8 * (s & 1) + 2 * e;
;                 f32x2 pv;
;                 pv.x = __builtin_amdgcn_exp2f(s < 2 ? S0[i] : S1[i]); pv.y = __builtin_amdgcn_exp2f(s < 2 ? S0[i + 1] : S1[i + 1]);
;                 ls2 = ls2 + pv;
;                 w[e] = pk2(pv.x, pv.y);
;             }
;             u32x4 wv; wv.x = w[0]; wv.y = w[1]; wv.z = w[2]; wv.w = w[3];
;             pf[s] = __builtin_bit_cast(bf16x8, wv);
;         }
;         l = l * alpha + (ls2.x + ls2.y);
;         if (__any(alpha != 1.0f)) {
; #pragma unroll
;             for (int blk = 0; blk < 4; ++blk) O[blk] = O[blk] * alpha;
;         }
;     };
;     auto pv_acc = [&](int st) __attribute__((always_inline)) {
;         LAS unsigned char* Vb = lds + st * A_STAGE;
; #pragma unroll
;         for (int s = 0; s < 4; ++s) {
; #pragma unroll
;             for (int blk = 0; blk < 4; ++blk) {
;                 const s16x4 lo = __builtin_amdgcn_ds_read_tr16_b64_v4i16((LAS s16x4*)(Vb + s * 4096 + voffs[blk][0]));
;                 const s16x4 hi = __builtin_amdgcn_ds_read_tr16_b64_v4i16((LAS s16x4*)(Vb + s * 4096 + voffs[blk][1]));
;                 const bf16x8 va = __builtin_shufflevector(lo, hi, 0, 1, 2, 3, 4, 5, 6, 7);
;                 O[blk] = MFMA32(va, pf[s], O[blk]);
;             }
;         }
.LBB0_239:
	v_pk_add_f32 v[94:95], v[96:97], v[14:15] op_sel_hi:[1,0] neg_lo:[0,1] neg_hi:[0,1]
	v_pk_add_f32 v[102:103], v[82:83], v[14:15] op_sel_hi:[1,0] neg_lo:[0,1] neg_hi:[0,1]
	v_pk_add_f32 v[82:83], v[100:101], v[14:15] op_sel_hi:[1,0] neg_lo:[0,1] neg_hi:[0,1]
	v_pk_add_f32 v[100:101], v[10:11], v[14:15] op_sel_hi:[1,0] neg_lo:[0,1] neg_hi:[0,1]
	v_exp_f32_e32 v10, v94
	v_exp_f32_e32 v11, v95
	v_pk_add_f32 v[98:99], v[98:99], v[14:15] op_sel_hi:[1,0] neg_lo:[0,1] neg_hi:[0,1]
	v_pk_add_f32 v[96:97], v[80:81], v[14:15] op_sel_hi:[1,0] neg_lo:[0,1] neg_hi:[0,1]
	v_pk_add_f32 v[12:13], v[12:13], v[14:15] op_sel_hi:[1,0] neg_lo:[0,1] neg_hi:[0,1]
	v_pk_add_f32 v[94:95], v[10:11], 0 op_sel_hi:[1,0]
	v_cvt_pk_bf16_f32 v80, v10, v11
	v_exp_f32_e32 v10, v98
	v_exp_f32_e32 v11, v99
	v_pk_add_f32 v[8:9], v[8:9], v[14:15] op_sel_hi:[1,0] neg_lo:[0,1] neg_hi:[0,1]
	v_pk_add_f32 v[6:7], v[6:7], v[14:15] op_sel_hi:[1,0] neg_lo:[0,1] neg_hi:[0,1]
	v_exp_f32_e32 v8, v8
	v_pk_add_f32 v[94:95], v[10:11], v[94:95]
	v_cvt_pk_bf16_f32 v81, v10, v11
	v_exp_f32_e32 v10, v82
	v_exp_f32_e32 v11, v83
	v_exp_f32_e32 v9, v9
	v_pk_add_f32 v[4:5], v[4:5], v[14:15] op_sel_hi:[1,0] neg_lo:[0,1] neg_hi:[0,1]
	v_exp_f32_e32 v6, v6
	v_pk_add_f32 v[94:95], v[10:11], v[94:95]
	v_cvt_pk_bf16_f32 v82, v10, v11
	v_exp_f32_e32 v10, v12
	v_exp_f32_e32 v11, v13
	v_exp_f32_e32 v7, v7
	v_pk_add_f32 v[2:3], v[2:3], v[14:15] op_sel_hi:[1,0] neg_lo:[0,1] neg_hi:[0,1]
	v_exp_f32_e32 v4, v4
	v_exp_f32_e32 v5, v5
	v_pk_add_f32 v[12:13], v[10:11], v[94:95]
	v_exp_f32_e32 v2, v2
	v_exp_f32_e32 v3, v3
	v_pk_add_f32 v[12:13], v[8:9], v[12:13]
	v_cvt_pk_bf16_f32 v83, v10, v11
	v_cvt_pk_bf16_f32 v10, v8, v9
	v_pk_add_f32 v[8:9], v[6:7], v[12:13]
	v_cvt_pk_bf16_f32 v11, v6, v7
	v_pk_add_f32 v[6:7], v[4:5], v[8:9]
	v_cvt_pk_bf16_f32 v12, v4, v5
	v_pk_add_f32 v[4:5], v[2:3], v[6:7]
	v_cvt_pk_bf16_f32 v13, v2, v3
	v_exp_f32_e32 v2, v96
	v_exp_f32_e32 v3, v97
	v_pk_add_f32 v[84:85], v[84:85], v[14:15] op_sel_hi:[1,0] neg_lo:[0,1] neg_hi:[0,1]
	v_pk_add_f32 v[86:87], v[86:87], v[14:15] op_sel_hi:[1,0] neg_lo:[0,1] neg_hi:[0,1]
	v_pk_add_f32 v[88:89], v[88:89], v[14:15] op_sel_hi:[1,0] neg_lo:[0,1] neg_hi:[0,1]
	v_pk_add_f32 v[4:5], v[2:3], v[4:5]
	v_cvt_pk_bf16_f32 v6, v2, v3
	v_exp_f32_e32 v2, v102
	v_exp_f32_e32 v3, v103
	v_pk_add_f32 v[90:91], v[90:91], v[14:15] op_sel_hi:[1,0] neg_lo:[0,1] neg_hi:[0,1]
	v_pk_add_f32 v[92:93], v[92:93], v[14:15] op_sel_hi:[1,0] neg_lo:[0,1] neg_hi:[0,1]
	v_add_u32_e32 v94, s44, v176
	v_pk_add_f32 v[4:5], v[2:3], v[4:5]
	v_cvt_pk_bf16_f32 v7, v2, v3
	v_exp_f32_e32 v2, v84
	v_exp_f32_e32 v3, v85
	v_exp_f32_e32 v84, v90
	v_exp_f32_e32 v85, v91
	v_add_u32_e32 v90, s44, v172
	v_pk_add_f32 v[4:5], v[2:3], v[4:5]
	v_cvt_pk_bf16_f32 v8, v2, v3
	v_exp_f32_e32 v2, v86
	v_exp_f32_e32 v3, v87
	v_add_u32_e32 v91, s44, v173
	v_pk_add_f32 v[4:5], v[2:3], v[4:5]
	v_cvt_pk_bf16_f32 v9, v2, v3
	v_exp_f32_e32 v2, v88
	v_exp_f32_e32 v3, v89
	v_add_u32_e32 v88, s44, v170
	v_add_u32_e32 v89, s44, v171
	v_pk_add_f32 v[4:5], v[2:3], v[4:5]
	v_cvt_pk_bf16_f32 v2, v2, v3
	v_pk_add_f32 v[4:5], v[84:85], v[4:5]
	v_cvt_pk_bf16_f32 v3, v84, v85
	v_exp_f32_e32 v84, v92
	v_exp_f32_e32 v85, v93
	v_add_u32_e32 v92, s44, v174
	v_add_u32_e32 v93, s44, v175
	v_pk_add_f32 v[86:87], v[84:85], v[4:5]
	v_cvt_pk_bf16_f32 v4, v84, v85
	v_exp_f32_e32 v84, v100
	v_exp_f32_e32 v85, v101
	s_nop 0
	v_pk_add_f32 v[86:87], v[84:85], v[86:87]
	s_nop 0
	v_add_f32_e32 v15, v86, v87
	v_fmac_f32_e32 v15, v180, v0
	v_add_u32_e32 v0, s44, v169
	v_cvt_pk_bf16_f32 v5, v84, v85
	ds_read_b64_tr_b16 v[192:193], v0 offset:16384
	ds_read_b64_tr_b16 v[194:195], v88 offset:2048
	ds_read_b64_tr_b16 v[196:197], v89 offset:16384
	ds_read_b64_tr_b16 v[198:199], v90 offset:2048
	s_waitcnt lgkmcnt(2)
	v_mfma_f32_32x32x16_bf16 v[64:79], v[192:195], v[80:83], v[64:79]
	ds_read_b64_tr_b16 v[192:193], v91 offset:16384
	ds_read_b64_tr_b16 v[194:195], v92 offset:2048
	v_mov_b32_e32 v180, v15
	s_waitcnt lgkmcnt(2)
	v_mfma_f32_32x32x16_bf16 v[48:63], v[196:199], v[80:83], v[48:63]
	ds_read_b64_tr_b16 v[196:197], v93 offset:16384
	ds_read_b64_tr_b16 v[198:199], v94 offset:2048
	s_waitcnt lgkmcnt(2)
	v_mfma_f32_32x32x16_bf16 v[32:47], v[192:195], v[80:83], v[32:47]
	ds_read_b64_tr_b16 v[192:193], v0 offset:20480
	ds_read_b64_tr_b16 v[194:195], v88 offset:6144
	s_waitcnt lgkmcnt(2)
	v_mfma_f32_32x32x16_bf16 v[16:31], v[196:199], v[80:83], v[16:31]
	ds_read_b64_tr_b16 v[196:197], v89 offset:20480
	ds_read_b64_tr_b16 v[198:199], v90 offset:6144
	s_waitcnt lgkmcnt(2)
	v_mfma_f32_32x32x16_bf16 v[64:79], v[192:195], v[10:13], v[64:79]
	ds_read_b64_tr_b16 v[192:193], v91 offset:20480
	ds_read_b64_tr_b16 v[194:195], v92 offset:6144
	s_waitcnt lgkmcnt(2)
	v_mfma_f32_32x32x16_bf16 v[48:63], v[196:199], v[10:13], v[48:63]
	ds_read_b64_tr_b16 v[196:197], v93 offset:20480
	ds_read_b64_tr_b16 v[198:199], v94 offset:6144
	s_waitcnt lgkmcnt(2)
	v_mfma_f32_32x32x16_bf16 v[32:47], v[192:195], v[10:13], v[32:47]
	ds_read_b64_tr_b16 v[192:193], v0 offset:24576
	ds_read_b64_tr_b16 v[194:195], v88 offset:10240
	s_waitcnt lgkmcnt(2)
	v_mfma_f32_32x32x16_bf16 v[16:31], v[196:199], v[10:13], v[16:31]
	ds_read_b64_tr_b16 v[196:197], v89 offset:24576
	ds_read_b64_tr_b16 v[198:199], v90 offset:10240
	s_waitcnt lgkmcnt(2)
	v_mfma_f32_32x32x16_bf16 v[64:79], v[192:195], v[6:9], v[64:79]
	ds_read_b64_tr_b16 v[192:193], v91 offset:24576
	ds_read_b64_tr_b16 v[194:195], v92 offset:10240
	s_waitcnt lgkmcnt(2)
	v_mfma_f32_32x32x16_bf16 v[48:63], v[196:199], v[6:9], v[48:63]
	ds_read_b64_tr_b16 v[196:197], v93 offset:24576
	ds_read_b64_tr_b16 v[198:199], v94 offset:10240
	s_waitcnt lgkmcnt(2)
	v_mfma_f32_32x32x16_bf16 v[32:47], v[192:195], v[6:9], v[32:47]
	ds_read_b64_tr_b16 v[192:193], v0 offset:28672
	ds_read_b64_tr_b16 v[194:195], v88 offset:14336
	s_waitcnt lgkmcnt(2)
	v_mfma_f32_32x32x16_bf16 v[16:31], v[196:199], v[6:9], v[16:31]
	ds_read_b64_tr_b16 v[196:197], v89 offset:28672
	ds_read_b64_tr_b16 v[198:199], v90 offset:14336
	s_waitcnt lgkmcnt(2)
	v_mfma_f32_32x32x16_bf16 v[64:79], v[192:195], v[2:5], v[64:79]
	ds_read_b64_tr_b16 v[192:193], v91 offset:28672
	ds_read_b64_tr_b16 v[194:195], v92 offset:14336
	s_waitcnt lgkmcnt(2)
	v_mfma_f32_32x32x16_bf16 v[48:63], v[196:199], v[2:5], v[48:63]
	ds_read_b64_tr_b16 v[196:197], v93 offset:28672
	ds_read_b64_tr_b16 v[198:199], v94 offset:14336
	s_waitcnt lgkmcnt(2)
	v_mfma_f32_32x32x16_bf16 v[32:47], v[192:195], v[2:5], v[32:47]
	s_waitcnt lgkmcnt(0)
	v_mfma_f32_32x32x16_bf16 v[16:31], v[196:199], v[2:5], v[16:31]
	s_cmp_gt_u32 s71, 4
	s_cbranch_scc0 .LBB0_241
	s_branch .LBB0_246

; #define LAS __attribute__((address_space(3)))
; __device__ __forceinline__ unsigned pk2(float lo, float hi) { f32x2 v = {lo, hi}; bf16x2_t b = __builtin_convertvector(v, bf16x2_t); return __builtin_bit_cast(unsigned, b); }
; #define MFMA32(a, b, c) __builtin_amdgcn_mfma_f32_32x32x16_bf16((a), (b), (c), 0, 0, 0)
; template <int KSTEPS, class Pol>
; __device__ __forceinline__ void attn_pass(LAS unsigned char* lds, const Pol& P, const bf16_t* qb, int ldq, const bf16_t* kb, int ldk, const bf16_t* vb, int ldv,
;                                           float qs, f32x16 (&O)[4], float& m, float& l) {
;     ...
;             const f32x2 nm = {-mnew, -mnew};
; #pragma unroll
;             for (int i = 0; i < 16; i += 2) { const f32x2 a = (f32x2){S0[i], S0[i + 1]} + nm, b = (f32x2){S1[i], S1[i + 1]} + nm; S0[i] = a.x; S0[i + 1] = a.y; S1[i] = b.x; S1[i + 1] = b.y; }
;         }
;         f32x2 ls2 = {0.f, 0.f};
; #pragma unroll
;         for (int s = 0; s < 4; ++s) {
;             unsigned w[4];
; #pragma unroll
;             for (int e = 0; e < 4; ++e) {
;                 const int i = 8 * (s & 1) + 2 * e;
;                 f32x2 pv;
;                 pv.x = __builtin_amdgcn_exp2f(s < 2 ? S0[i] : S1[i]); pv.y = __builtin_amdgcn_exp2f(s < 2 ? S0[i + 1] : S1[i + 1]);
;                 ls2 = ls2 + pv;
;                 w[e] = pk2(pv.x, pv.y);
;             }
;             u32x4 wv; wv.x = w[0]; wv.y = w[1]; wv.z = w[2]; wv.w = w[3];
;             pf[s] = __builtin_bit_cast(bf16x8, wv);
;         }
;         l = l * alpha + (ls2.x + ls2.y);
;         if (__any(alpha != 1.0f)) {
; #pragma unroll
;             for (int blk = 0; blk < 4; ++blk) O[blk] = O[blk] * alpha;
;         }
;     };
;     auto pv_acc = [&](int st) __attribute__((always_inline)) {
;         LAS unsigned char* Vb = lds + st * A_STAGE;
; #pragma unroll
;         for (int s = 0; s < 4; ++s) {
; #pragma unroll
;             for (int blk = 0; blk < 4; ++blk) {
;                 const s16x4 lo = __builtin_amdgcn_ds_read_tr16_b64_v4i16((LAS s16x4*)(Vb + s * 4096 + voffs[blk][0]));
;                 const s16x4 hi = __builtin_amdgcn_ds_read_tr16_b64_v4i16((LAS s16x4*)(Vb + s * 4096 + voffs[blk][1]));
;                 const bf16x8 va = __builtin_shufflevector(lo, hi, 0, 1, 2, 3, 4, 5, 6, 7);
;                 O[blk] = MFMA32(va, pf[s], O[blk]);
;             }
;         }
.LBB0_466:
	v_pk_add_f32 v[92:93], v[96:97], v[0:1] op_sel_hi:[1,0] neg_lo:[0,1] neg_hi:[0,1]
	v_pk_add_f32 v[104:105], v[8:9], v[0:1] op_sel_hi:[1,0] neg_lo:[0,1] neg_hi:[0,1]
	v_exp_f32_e32 v8, v92
	v_exp_f32_e32 v9, v93
	v_pk_add_f32 v[96:97], v[98:99], v[0:1] op_sel_hi:[1,0] neg_lo:[0,1] neg_hi:[0,1]
	v_pk_add_f32 v[94:95], v[80:81], v[0:1] op_sel_hi:[1,0] neg_lo:[0,1] neg_hi:[0,1]
	v_pk_add_f32 v[98:99], v[82:83], v[0:1] op_sel_hi:[1,0] neg_lo:[0,1] neg_hi:[0,1]
	v_pk_add_f32 v[82:83], v[100:101], v[0:1] op_sel_hi:[1,0] neg_lo:[0,1] neg_hi:[0,1]
	v_pk_add_f32 v[100:101], v[102:103], v[0:1] op_sel_hi:[1,0] neg_lo:[0,1] neg_hi:[0,1]
	v_pk_add_f32 v[102:103], v[12:13], v[0:1] op_sel_hi:[1,0] neg_lo:[0,1] neg_hi:[0,1]
	v_pk_add_f32 v[12:13], v[8:9], 0 op_sel_hi:[1,0]
	v_cvt_pk_bf16_f32 v80, v8, v9
	v_exp_f32_e32 v8, v96
	v_exp_f32_e32 v9, v97
	v_pk_add_f32 v[10:11], v[10:11], v[0:1] op_sel_hi:[1,0] neg_lo:[0,1] neg_hi:[0,1]
	v_pk_add_f32 v[6:7], v[6:7], v[0:1] op_sel_hi:[1,0] neg_lo:[0,1] neg_hi:[0,1]
	v_pk_add_f32 v[4:5], v[4:5], v[0:1] op_sel_hi:[1,0] neg_lo:[0,1] neg_hi:[0,1]
	v_pk_add_f32 v[12:13], v[8:9], v[12:13]
	v_cvt_pk_bf16_f32 v81, v8, v9
	v_exp_f32_e32 v8, v82
	v_exp_f32_e32 v9, v83
	v_exp_f32_e32 v6, v6
	v_exp_f32_e32 v7, v7
	v_pk_add_f32 v[2:3], v[2:3], v[0:1] op_sel_hi:[1,0] neg_lo:[0,1] neg_hi:[0,1]
	v_pk_add_f32 v[12:13], v[8:9], v[12:13]
	v_cvt_pk_bf16_f32 v82, v8, v9
	v_exp_f32_e32 v8, v100
	v_exp_f32_e32 v9, v101
	v_exp_f32_e32 v4, v4
	v_exp_f32_e32 v5, v5
	v_exp_f32_e32 v2, v2
	v_pk_add_f32 v[12:13], v[8:9], v[12:13]
	v_cvt_pk_bf16_f32 v83, v8, v9
	v_exp_f32_e32 v8, v10
	v_exp_f32_e32 v9, v11
	v_exp_f32_e32 v3, v3
	v_cvt_pk_bf16_f32 v11, v6, v7
	v_pk_add_f32 v[84:85], v[84:85], v[0:1] op_sel_hi:[1,0] neg_lo:[0,1] neg_hi:[0,1]
	v_pk_add_f32 v[12:13], v[8:9], v[12:13]
	v_cvt_pk_bf16_f32 v10, v8, v9
	v_pk_add_f32 v[8:9], v[6:7], v[12:13]
	v_cvt_pk_bf16_f32 v12, v4, v5
	v_pk_add_f32 v[6:7], v[4:5], v[8:9]
	v_cvt_pk_bf16_f32 v13, v2, v3
	v_pk_add_f32 v[4:5], v[2:3], v[6:7]
	v_exp_f32_e32 v2, v94
	v_exp_f32_e32 v3, v95
	v_pk_add_f32 v[86:87], v[86:87], v[0:1] op_sel_hi:[1,0] neg_lo:[0,1] neg_hi:[0,1]
	v_pk_add_f32 v[88:89], v[88:89], v[0:1] op_sel_hi:[1,0] neg_lo:[0,1] neg_hi:[0,1]
	v_pk_add_f32 v[90:91], v[90:91], v[0:1] op_sel_hi:[1,0] neg_lo:[0,1] neg_hi:[0,1]
	v_pk_add_f32 v[4:5], v[2:3], v[4:5]
	v_cvt_pk_bf16_f32 v6, v2, v3
	v_exp_f32_e32 v2, v98
	v_exp_f32_e32 v3, v99
	v_add_u32_e32 v92, s51, v169
	v_add_u32_e32 v93, s51, v170
	v_add_u32_e32 v94, s51, v171
	v_pk_add_f32 v[4:5], v[2:3], v[4:5]
	v_cvt_pk_bf16_f32 v7, v2, v3
	v_exp_f32_e32 v2, v84
	v_exp_f32_e32 v3, v85
	v_exp_f32_e32 v84, v90
	v_exp_f32_e32 v85, v91
	v_add_u32_e32 v90, s51, v167
	v_pk_add_f32 v[4:5], v[2:3], v[4:5]
	v_cvt_pk_bf16_f32 v8, v2, v3
	v_exp_f32_e32 v2, v86
	v_exp_f32_e32 v3, v87
	v_add_u32_e32 v91, s51, v168
	v_pk_add_f32 v[4:5], v[2:3], v[4:5]
	v_cvt_pk_bf16_f32 v9, v2, v3
	v_exp_f32_e32 v2, v88
	v_exp_f32_e32 v3, v89
	v_add_u32_e32 v88, s51, v165
	v_add_u32_e32 v89, s51, v166
	v_pk_add_f32 v[4:5], v[2:3], v[4:5]
	v_cvt_pk_bf16_f32 v2, v2, v3
	v_pk_add_f32 v[4:5], v[84:85], v[4:5]
	v_cvt_pk_bf16_f32 v3, v84, v85
	v_exp_f32_e32 v84, v102
	v_exp_f32_e32 v85, v103
	s_nop 0
	v_pk_add_f32 v[86:87], v[84:85], v[4:5]
	v_cvt_pk_bf16_f32 v4, v84, v85
	v_exp_f32_e32 v84, v104
	v_exp_f32_e32 v85, v105
	s_nop 0
	v_pk_add_f32 v[86:87], v[84:85], v[86:87]
	s_nop 0
	v_add_f32_e32 v15, v86, v87
	v_fmac_f32_e32 v15, v174, v14
	v_add_u32_e32 v14, s51, v164
	v_cvt_pk_bf16_f32 v5, v84, v85
	ds_read_b64_tr_b16 v[192:193], v14 offset:16384
	ds_read_b64_tr_b16 v[194:195], v88 offset:2048
	ds_read_b64_tr_b16 v[196:197], v89 offset:16384
	ds_read_b64_tr_b16 v[198:199], v90 offset:2048
	s_waitcnt lgkmcnt(2)
	v_mfma_f32_32x32x16_bf16 v[64:79], v[192:195], v[80:83], v[64:79]
	ds_read_b64_tr_b16 v[192:193], v91 offset:16384
	ds_read_b64_tr_b16 v[194:195], v92 offset:2048
	v_mov_b32_e32 v174, v15
	s_waitcnt lgkmcnt(2)
	v_mfma_f32_32x32x16_bf16 v[48:63], v[196:199], v[80:83], v[48:63]
	ds_read_b64_tr_b16 v[196:197], v93 offset:16384
	ds_read_b64_tr_b16 v[198:199], v94 offset:2048
	s_waitcnt lgkmcnt(2)
	v_mfma_f32_32x32x16_bf16 v[32:47], v[192:195], v[80:83], v[32:47]
	ds_read_b64_tr_b16 v[192:193], v14 offset:20480
	ds_read_b64_tr_b16 v[194:195], v88 offset:6144
	s_waitcnt lgkmcnt(2)
	v_mfma_f32_32x32x16_bf16 v[16:31], v[196:199], v[80:83], v[16:31]
	ds_read_b64_tr_b16 v[196:197], v89 offset:20480
	ds_read_b64_tr_b16 v[198:199], v90 offset:6144
	s_waitcnt lgkmcnt(2)
	v_mfma_f32_32x32x16_bf16 v[64:79], v[192:195], v[10:13], v[64:79]
	ds_read_b64_tr_b16 v[192:193], v91 offset:20480
	ds_read_b64_tr_b16 v[194:195], v92 offset:6144
	s_waitcnt lgkmcnt(2)
	v_mfma_f32_32x32x16_bf16 v[48:63], v[196:199], v[10:13], v[48:63]
	ds_read_b64_tr_b16 v[196:197], v93 offset:20480
	ds_read_b64_tr_b16 v[198:199], v94 offset:6144
	s_waitcnt lgkmcnt(2)
	v_mfma_f32_32x32x16_bf16 v[32:47], v[192:195], v[10:13], v[32:47]
	ds_read_b64_tr_b16 v[192:193], v14 offset:24576
	ds_read_b64_tr_b16 v[194:195], v88 offset:10240
	s_waitcnt lgkmcnt(2)
	v_mfma_f32_32x32x16_bf16 v[16:31], v[196:199], v[10:13], v[16:31]
	ds_read_b64_tr_b16 v[196:197], v89 offset:24576
	ds_read_b64_tr_b16 v[198:199], v90 offset:10240
	s_waitcnt lgkmcnt(2)
	v_mfma_f32_32x32x16_bf16 v[64:79], v[192:195], v[6:9], v[64:79]
	ds_read_b64_tr_b16 v[192:193], v91 offset:24576
	ds_read_b64_tr_b16 v[194:195], v92 offset:10240
	s_waitcnt lgkmcnt(2)
	v_mfma_f32_32x32x16_bf16 v[48:63], v[196:199], v[6:9], v[48:63]
	ds_read_b64_tr_b16 v[196:197], v93 offset:24576
	ds_read_b64_tr_b16 v[198:199], v94 offset:10240
	s_waitcnt lgkmcnt(2)
	v_mfma_f32_32x32x16_bf16 v[32:47], v[192:195], v[6:9], v[32:47]
	ds_read_b64_tr_b16 v[192:193], v14 offset:28672
	ds_read_b64_tr_b16 v[194:195], v88 offset:14336
	s_waitcnt lgkmcnt(2)
	v_mfma_f32_32x32x16_bf16 v[16:31], v[196:199], v[6:9], v[16:31]
	ds_read_b64_tr_b16 v[196:197], v89 offset:28672
	ds_read_b64_tr_b16 v[198:199], v90 offset:14336
	s_waitcnt lgkmcnt(2)
	v_mfma_f32_32x32x16_bf16 v[64:79], v[192:195], v[2:5], v[64:79]
	ds_read_b64_tr_b16 v[192:193], v91 offset:28672
	ds_read_b64_tr_b16 v[194:195], v92 offset:14336
	s_waitcnt lgkmcnt(2)
	v_mfma_f32_32x32x16_bf16 v[48:63], v[196:199], v[2:5], v[48:63]
	ds_read_b64_tr_b16 v[196:197], v93 offset:28672
	ds_read_b64_tr_b16 v[198:199], v94 offset:14336
	s_waitcnt lgkmcnt(2)
	v_mfma_f32_32x32x16_bf16 v[32:47], v[192:195], v[2:5], v[32:47]
	s_waitcnt lgkmcnt(0)
	v_mfma_f32_32x32x16_bf16 v[16:31], v[196:199], v[2:5], v[16:31]
	s_cmp_ge_i32 s49, s45
	s_cbranch_scc0 .LBB0_468
	s_branch .LBB0_473

; #define LAS __attribute__((address_space(3)))
; __device__ __forceinline__ unsigned pk2(float lo, float hi) { f32x2 v = {lo, hi}; bf16x2_t b = __builtin_convertvector(v, bf16x2_t); return __builtin_bit_cast(unsigned, b); }
; #define MFMA32(a, b, c) __builtin_amdgcn_mfma_f32_32x32x16_bf16((a), (b), (c), 0, 0, 0)
; template <int KSTEPS, class Pol>
; __device__ __forceinline__ void attn_pass(LAS unsigned char* lds, const Pol& P, const bf16_t* qb, int ldq, const bf16_t* kb, int ldk, const bf16_t* vb, int ldv,
;                                           float qs, f32x16 (&O)[4], float& m, float& l) {
;     ...
;             const f32x2 nm = {-mnew, -mnew};
; #pragma unroll
;             for (int i = 0; i < 16; i += 2) { const f32x2 a = (f32x2){S0[i], S0[i + 1]} + nm, b = (f32x2){S1[i], S1[i + 1]} + nm; S0[i] = a.x; S0[i + 1] = a.y; S1[i] = b.x; S1[i + 1] = b.y; }
;         }
;         f32x2 ls2 = {0.f, 0.f};
; #pragma unroll
;         for (int s = 0; s < 4; ++s) {
;             unsigned w[4];
; #pragma unroll
;             for (int e = 0; e < 4; ++e) {
;                 const int i = 8 * (s & 1) + 2 * e;
;                 f32x2 pv;
;                 pv.x = __builtin_amdgcn_exp2f(s < 2 ? S0[i] : S1[i]); pv.y = __builtin_amdgcn_exp2f(s < 2 ? S0[i + 1] : S1[i + 1]);
;                 ls2 = ls2 + pv;
;                 w[e] = pk2(pv.x, pv.y);
;             }
;             u32x4 wv; wv.x = w[0]; wv.y = w[1]; wv.z = w[2]; wv.w = w[3];
;             pf[s] = __builtin_bit_cast(bf16x8, wv);
;         }
;         l = l * alpha + (ls2.x + ls2.y);
;         if (__any(alpha != 1.0f)) {
; #pragma unroll
;             for (int blk = 0; blk < 4; ++blk) O[blk] = O[blk] * alpha;
;         }
;     };
;     auto pv_acc = [&](int st) __attribute__((always_inline)) {
;         LAS unsigned char* Vb = lds + st * A_STAGE;
; #pragma unroll
;         for (int s = 0; s < 4; ++s) {
; #pragma unroll
;             for (int blk = 0; blk < 4; ++blk) {
;                 const s16x4 lo = __builtin_amdgcn_ds_read_tr16_b64_v4i16((LAS s16x4*)(Vb + s * 4096 + voffs[blk][0]));
;                 const s16x4 hi = __builtin_amdgcn_ds_read_tr16_b64_v4i16((LAS s16x4*)(Vb + s * 4096 + voffs[blk][1]));
;                 const bf16x8 va = __builtin_shufflevector(lo, hi, 0, 1, 2, 3, 4, 5, 6, 7);
;                 O[blk] = MFMA32(va, pf[s], O[blk]);
;             }
;         }
.LBB0_507:
	v_add_u32_e32 v7, s36, v158
	v_add_u32_e32 v139, s36, v159
	ds_read_b64_tr_b16 v[80:81], v7 offset:16384
	ds_read_b64_tr_b16 v[82:83], v139 offset:2048
	v_pk_add_f32 v[14:15], v[14:15], v[0:1] op_sel_hi:[1,0] neg_lo:[0,1] neg_hi:[0,1]
	v_pk_add_f32 v[12:13], v[12:13], v[0:1] op_sel_hi:[1,0] neg_lo:[0,1] neg_hi:[0,1]
	v_pk_add_f32 v[84:85], v[10:11], v[0:1] op_sel_hi:[1,0] neg_lo:[0,1] neg_hi:[0,1]
	v_pk_add_f32 v[100:101], v[8:9], v[0:1] op_sel_hi:[1,0] neg_lo:[0,1] neg_hi:[0,1]
	v_exp_f32_e32 v8, v14
	v_exp_f32_e32 v9, v15
	v_exp_f32_e32 v10, v12
	v_exp_f32_e32 v11, v13
	v_exp_f32_e32 v12, v84
	v_exp_f32_e32 v13, v85
	v_exp_f32_e32 v14, v100
	v_exp_f32_e32 v15, v101
	v_cvt_pk_bf16_f32 v100, v8, v9
	v_cvt_pk_bf16_f32 v101, v10, v11
	v_cvt_pk_bf16_f32 v102, v12, v13
	v_cvt_pk_bf16_f32 v103, v14, v15
	v_add_u32_e32 v167, s36, v160
	v_add_u32_e32 v168, s36, v161
	v_pk_add_f32 v[84:85], v[146:147], v[0:1] op_sel_hi:[1,0] neg_lo:[0,1] neg_hi:[0,1]
	v_add_u32_e32 v146, s36, v162
	v_add_u32_e32 v147, s36, v163
	ds_read_b64_tr_b16 v[104:105], v146 offset:16384
	ds_read_b64_tr_b16 v[106:107], v147 offset:2048
	s_waitcnt lgkmcnt(2)
	v_mfma_f32_32x32x16_bf16 v[64:79], v[80:83], v[100:103], v[64:79]
	ds_read_b64_tr_b16 v[80:81], v167 offset:16384
	ds_read_b64_tr_b16 v[82:83], v168 offset:2048
	v_add_u32_e32 v169, s36, v164
	v_add_u32_e32 v170, s36, v165
	ds_read_b64_tr_b16 v[108:109], v169 offset:16384
	ds_read_b64_tr_b16 v[110:111], v170 offset:2048
	v_pk_add_f32 v[142:143], v[142:143], v[0:1] op_sel_hi:[1,0] neg_lo:[0,1] neg_hi:[0,1]
	s_waitcnt lgkmcnt(2)
	v_mfma_f32_32x32x16_bf16 v[48:63], v[80:83], v[100:103], v[48:63]
	v_add_f32_e64 v82, v90, -v0
	v_add_f32_e64 v83, v91, -v0
	v_add_f32_e64 v90, v144, -v0
	v_add_f32_e64 v91, v145, -v0
	v_exp_f32_e32 v80, v84
	v_exp_f32_e32 v81, v85
	v_exp_f32_e32 v82, v82
	v_exp_f32_e32 v83, v83
	v_exp_f32_e32 v84, v90
	v_mfma_f32_32x32x16_bf16 v[32:47], v[104:107], v[100:103], v[32:47]
	ds_read_b64_tr_b16 v[104:105], v7 offset:20480
	ds_read_b64_tr_b16 v[106:107], v139 offset:6144
	v_exp_f32_e32 v85, v91
	v_exp_f32_e32 v90, v142
	v_exp_f32_e32 v91, v143
	v_pk_add_f32 v[96:97], v[96:97], v[0:1] op_sel_hi:[1,0] neg_lo:[0,1] neg_hi:[0,1]
	v_pk_add_f32 v[98:99], v[98:99], v[0:1] op_sel_hi:[1,0] neg_lo:[0,1] neg_hi:[0,1]
	v_pk_add_f32 v[142:143], v[94:95], v[0:1] op_sel_hi:[1,0] neg_lo:[0,1] neg_hi:[0,1]
	s_waitcnt lgkmcnt(2)
	v_mfma_f32_32x32x16_bf16 v[16:31], v[108:111], v[100:103], v[16:31]
	v_cvt_pk_bf16_f32 v100, v80, v81
	v_cvt_pk_bf16_f32 v101, v82, v83
	v_cvt_pk_bf16_f32 v102, v84, v85
	v_cvt_pk_bf16_f32 v103, v90, v91
	v_add_f32_e64 v144, v92, -v0
	v_add_f32_e64 v145, v93, -v0
	v_exp_f32_e32 v92, v96
	v_exp_f32_e32 v93, v97
	s_waitcnt lgkmcnt(0)
	v_mfma_f32_32x32x16_bf16 v[64:79], v[104:107], v[100:103], v[64:79]
	ds_read_b64_tr_b16 v[104:105], v167 offset:20480
	ds_read_b64_tr_b16 v[106:107], v168 offset:6144
	v_exp_f32_e32 v94, v98
	v_exp_f32_e32 v95, v99
	v_exp_f32_e32 v96, v142
	v_exp_f32_e32 v97, v143
	v_exp_f32_e32 v98, v144
	v_exp_f32_e32 v99, v145
	s_waitcnt lgkmcnt(0)
	v_mfma_f32_32x32x16_bf16 v[48:63], v[104:107], v[100:103], v[48:63]
	ds_read_b64_tr_b16 v[104:105], v146 offset:20480
	ds_read_b64_tr_b16 v[106:107], v147 offset:6144
	ds_read_b64_tr_b16 v[108:109], v169 offset:20480
	ds_read_b64_tr_b16 v[110:111], v170 offset:6144
	v_add_f32_e64 v88, v88, -v0
	v_add_f32_e64 v89, v89, -v0
	v_pk_add_f32 v[142:143], v[4:5], v[0:1] op_sel_hi:[1,0] neg_lo:[0,1] neg_hi:[0,1]
	v_pk_add_f32 v[144:145], v[2:3], v[0:1] op_sel_hi:[1,0] neg_lo:[0,1] neg_hi:[0,1]
	s_add_i32 s48, s48, 1
	s_cmp_ge_i32 s48, s44
	s_waitcnt lgkmcnt(2)
	v_mfma_f32_32x32x16_bf16 v[32:47], v[104:107], v[100:103], v[32:47]
	ds_read_b64_tr_b16 v[104:105], v7 offset:24576
	ds_read_b64_tr_b16 v[106:107], v139 offset:10240
	s_waitcnt lgkmcnt(2)
	v_mfma_f32_32x32x16_bf16 v[16:31], v[108:111], v[100:103], v[16:31]
	ds_read_b64_tr_b16 v[100:101], v167 offset:24576
	ds_read_b64_tr_b16 v[102:103], v168 offset:10240
	v_cvt_pk_bf16_f32 v108, v92, v93
	v_cvt_pk_bf16_f32 v109, v94, v95
	v_cvt_pk_bf16_f32 v110, v96, v97
	v_cvt_pk_bf16_f32 v111, v98, v99
	s_waitcnt lgkmcnt(0)
	s_nop 0
	v_mfma_f32_32x32x16_bf16 v[48:63], v[100:103], v[108:111], v[48:63]
	ds_read_b64_tr_b16 v[100:101], v146 offset:24576
	ds_read_b64_tr_b16 v[102:103], v147 offset:10240
	ds_read_b64_tr_b16 v[2:3], v169 offset:24576
	ds_read_b64_tr_b16 v[4:5], v170 offset:10240
	v_mfma_f32_32x32x16_bf16 v[64:79], v[104:107], v[108:111], v[64:79]
	v_add_f32_e64 v104, v86, -v0
	v_add_f32_e64 v105, v87, -v0
	v_exp_f32_e32 v86, v88
	v_exp_f32_e32 v87, v89
	v_exp_f32_e32 v88, v104
	v_exp_f32_e32 v89, v105
	ds_read_b64_tr_b16 v[104:105], v7 offset:28672
	ds_read_b64_tr_b16 v[106:107], v139 offset:14336
	s_waitcnt lgkmcnt(4)
	v_mfma_f32_32x32x16_bf16 v[32:47], v[100:103], v[108:111], v[32:47]
	v_exp_f32_e32 v100, v142
	v_exp_f32_e32 v101, v143
	v_exp_f32_e32 v102, v144
	v_exp_f32_e32 v103, v145
	s_waitcnt lgkmcnt(2)
	v_mfma_f32_32x32x16_bf16 v[16:31], v[2:5], v[108:111], v[16:31]
	ds_read_b64_tr_b16 v[192:193], v167 offset:28672
	ds_read_b64_tr_b16 v[194:195], v168 offset:14336
	ds_read_b64_tr_b16 v[196:197], v146 offset:28672
	ds_read_b64_tr_b16 v[198:199], v147 offset:14336
	ds_read_b64_tr_b16 v[200:201], v169 offset:28672
	ds_read_b64_tr_b16 v[202:203], v170 offset:14336
	v_cvt_pk_bf16_f32 v2, v86, v87
	v_cvt_pk_bf16_f32 v3, v88, v89
	v_cvt_pk_bf16_f32 v4, v100, v101
	v_cvt_pk_bf16_f32 v5, v102, v103
	s_waitcnt lgkmcnt(6)
	s_nop 0
	v_mfma_f32_32x32x16_bf16 v[64:79], v[104:107], v[2:5], v[64:79]
	s_waitcnt lgkmcnt(4)
	v_mfma_f32_32x32x16_bf16 v[48:63], v[192:195], v[2:5], v[48:63]
	s_waitcnt lgkmcnt(2)
	v_mfma_f32_32x32x16_bf16 v[32:47], v[196:199], v[2:5], v[32:47]
	s_waitcnt lgkmcnt(0)
	v_mfma_f32_32x32x16_bf16 v[16:31], v[200:203], v[2:5], v[16:31]
	s_cbranch_scc1 .LBB0_513
	s_mov_b64 s[36:37], -1
	s_and_b64 vcc, exec, s[2:3]
	s_cbranch_vccz .LBB0_510
	s_waitcnt vmcnt(0)
	s_mov_b64 s[36:37], 0
